# new hand-scheduled weight-conversion loop (gains prefetched, batched LDS reads, next-tile prefetch); w_up+w_out+half w_down converted in P1 slack, rest of w_down in P2
# speedup vs baseline: 1.0169x; 1.0056x over previous
; #define LAS __attribute__((address_space(3)))
; __device__ __forceinline__ void transpose_tile(const float* __restrict__ W, int K, int N, bf16* __restrict__ WT, const float* __restrict__ ga, const float* __restrict__ gb, int gsplit, LAS float* scr, int item, int lane) {
;     const int nkb = K / 64, nb = item / nkb, kb = item % nkb, k0 = 64 * kb, n0 = 64 * nb;
;     const int c = lane & 15, kq = lane >> 4;
;     f32x4 v[16];
; #pragma unroll
;     for (int i = 0; i < 16; ++i) v[i] = __builtin_nontemporal_load((const f32x4*)(W + (size_t)(k0 + 4 * i + kq) * N + n0 + 4 * c));
; __global__ void __launch_bounds__(NT, 2) fwd_mega(Args A) {
;     ...
;         for (int it = gw; it < I_IN; it += NGW) transpose_tile(A.w_in, D, INW, WinT, A.g_mix, A.g_mix, D, scr, it, lane);
.LBB0_24:
	v_writelane_b32 v255, s54, 1
	s_nop 1
	v_writelane_b32 v255, s55, 2
	s_add_u32 s54, s28, 0x300000
	s_addc_u32 s55, s29, 0
	s_lshr_b32 s1, s58, 6
	s_lshl_b32 s0, s3, 3
	s_add_i32 s58, s0, s1
	s_mul_i32 s0, s1, 0x4100
	s_lshl_b32 s52, s30, 3
	v_writelane_b32 v255, s1, 3
	s_add_i32 s0, s0, 0
	v_writelane_b32 v255, s0, 4
	s_cmpk_gt_i32 s58, 0x6ff
	v_and_b32_e32 v152, 63, v160
	s_mov_b32 s60, s58
	s_mov_b32 s61, s52
	s_movk_i32 s62, 0x700
	s_cmp_ge_u32 s60, s62
	s_cbranch_scc1 .Lcva_end
	v_readlane_b32 s63, v255, 3
	v_and_b32_e32 v122, 63, v160
	v_and_b32_e32 v112, 15, v122
	v_lshlrev_b32_e32 v112, 4, v112
	v_lshrrev_b32_e32 v113, 4, v122
	v_lshlrev_b32_e32 v114, 2, v113
	v_and_b32_e32 v115, 7, v122
	v_lshrrev_b32_e32 v116, 3, v122
	s_mulk_i32 s63, 0x4100
	s_movk_i32 s80, 0x104
	v_mad_u32_u24 v117, v113, s80, v112
	v_add_u32_e32 v117, s63, v117
	s_movk_i32 s80, 0x820
	v_lshlrev_b32_e32 v119, 2, v116
	v_mad_u32_u24 v118, v115, s80, v119
	v_add_u32_e32 v118, s63, v118
	v_add_u32_e32 v119, 0x400, v118
	v_lshlrev_b32_e32 v115, 4, v115
	s_mov_b32 s75, s60
	s_branch .Lcva_p0_m0
.Lcva_p0_m0:
	s_mov_b32 s80, s75
	s_lshr_b32 s81, s80, 5
	s_and_b32 s82, s80, 0x1f
	s_lshl_b32 s81, s81, 6
	s_lshl_b32 s82, s82, 6
	s_mul_i32 s83, s82, 0xe00
	s_add_u32 s83, s83, s81
	s_lshl_b32 s83, s83, 2
	s_add_u32 s64, s42, s83
	s_addc_u32 s65, s43, 0
	s_lshl_b32 s84, s81, 11
	s_add_u32 s84, s84, s82
	s_lshl_b32 s84, s84, 1
	s_add_u32 s84, s84, 0x300000
	s_add_u32 s76, s28, s84
	s_addc_u32 s77, s29, 0
	s_mov_b32 s70, 0xe000
	s_mov_b32 s78, 0x8000
	s_mov_b32 s72, 0x3800
	s_mov_b32 s85, 0x1000
	s_mov_b32 s79, 1
	s_lshl_b32 s86, s82, 2
	s_add_u32 s68, s40, s86
	s_addc_u32 s69, s41, 0
	v_mad_u32_u24 v120, v113, s72, v112
	v_mad_u32_u24 v124, v116, s85, v115
.Lcva_p0_pd:
	s_cmp_eq_u32 s79, 0
	s_cbranch_scc1 .Lcva_p0_ng
	global_load_dword v64, v114, s[68:69]
	global_load_dword v65, v114, s[68:69] offset:16
	global_load_dword v66, v114, s[68:69] offset:32
	global_load_dword v67, v114, s[68:69] offset:48
	global_load_dword v68, v114, s[68:69] offset:64
	global_load_dword v69, v114, s[68:69] offset:80
	global_load_dword v70, v114, s[68:69] offset:96
	global_load_dword v71, v114, s[68:69] offset:112
	global_load_dword v72, v114, s[68:69] offset:128
	global_load_dword v73, v114, s[68:69] offset:144
	global_load_dword v74, v114, s[68:69] offset:160
	global_load_dword v75, v114, s[68:69] offset:176
	global_load_dword v76, v114, s[68:69] offset:192
	global_load_dword v77, v114, s[68:69] offset:208
	global_load_dword v78, v114, s[68:69] offset:224
	global_load_dword v79, v114, s[68:69] offset:240
.Lcva_p0_ng:
	global_load_dwordx4 v[0:3], v120, s[64:65] nt
	v_add_u32_e32 v120, s70, v120
	global_load_dwordx4 v[4:7], v120, s[64:65] nt
	v_add_u32_e32 v120, s70, v120
	global_load_dwordx4 v[8:11], v120, s[64:65] nt
	v_add_u32_e32 v120, s70, v120
	global_load_dwordx4 v[12:15], v120, s[64:65] nt
	v_add_u32_e32 v120, s70, v120
	global_load_dwordx4 v[16:19], v120, s[64:65] nt
	v_add_u32_e32 v120, s70, v120
	global_load_dwordx4 v[20:23], v120, s[64:65] nt
	v_add_u32_e32 v120, s70, v120
	global_load_dwordx4 v[24:27], v120, s[64:65] nt
	v_add_u32_e32 v120, s70, v120
	global_load_dwordx4 v[28:31], v120, s[64:65] nt
	v_add_u32_e32 v120, s70, v120
	global_load_dwordx4 v[32:35], v120, s[64:65] nt
	v_add_u32_e32 v120, s70, v120
	global_load_dwordx4 v[36:39], v120, s[64:65] nt
	v_add_u32_e32 v120, s70, v120
	global_load_dwordx4 v[40:43], v120, s[64:65] nt
	v_add_u32_e32 v120, s70, v120
	global_load_dwordx4 v[44:47], v120, s[64:65] nt
	v_add_u32_e32 v120, s70, v120
	global_load_dwordx4 v[48:51], v120, s[64:65] nt
	v_add_u32_e32 v120, s70, v120
	global_load_dwordx4 v[52:55], v120, s[64:65] nt
	v_add_u32_e32 v120, s70, v120
	global_load_dwordx4 v[56:59], v120, s[64:65] nt
	v_add_u32_e32 v120, s70, v120
	global_load_dwordx4 v[60:63], v120, s[64:65] nt
	global_load_dword v125, v114, s[28:29]
	global_load_dword v126, v114, s[28:29]
	global_load_dword v127, v114, s[28:29]
	global_load_dword v128, v114, s[28:29]
	global_load_dword v129, v114, s[28:29]
	global_load_dword v130, v114, s[28:29]
	global_load_dword v131, v114, s[28:29]
	global_load_dword v132, v114, s[28:29]
; #define LAS __attribute__((address_space(3)))
; #define LDS_WAIT() asm volatile("s_waitcnt lgkmcnt(0)" ::: "memory")
; __device__ __forceinline__ void transpose_tile(const float* __restrict__ W, int K, int N, bf16* __restrict__ WT, const float* __restrict__ ga, const float* __restrict__ gb, int gsplit, LAS float* scr, int item, int lane) {
;     ...
; #pragma unroll
;     for (int i = 0; i < 16; ++i) {
;         const int k = k0 + 4 * i + kq; float g = 1.0f; if (ga) g = (k < gsplit) ? ga[k] : gb[k - gsplit];
;         LAS float* p = scr + (4 * i + kq) * 65 + 4 * c; p[0] = v[i][0] * g; p[1] = v[i][1] * g; p[2] = v[i][2] * g; p[3] = v[i][3] * g;
;     }
;     LDS_WAIT(); asm volatile("" ::: "memory");
.Lcva_tile:
	s_mov_b64 s[66:67], s[76:77]
	s_mov_b32 s71, s78
	s_mov_b32 s74, s79
	v_mov_b32_e32 v121, v124
	s_cmp_eq_u32 s74, 0
	s_cbranch_scc1 .Lcva_wng
	s_waitcnt vmcnt(23)
	v_mul_f32_e32 v0, v64, v0
	v_mul_f32_e32 v1, v64, v1
	v_mul_f32_e32 v2, v64, v2
	v_mul_f32_e32 v3, v64, v3
	ds_write2_b32 v117, v0, v1 offset1:1
	ds_write2_b32 v117, v2, v3 offset0:2 offset1:3
	s_waitcnt vmcnt(22)
	v_mul_f32_e32 v4, v65, v4
	v_mul_f32_e32 v5, v65, v5
	v_mul_f32_e32 v6, v65, v6
	v_mul_f32_e32 v7, v65, v7
	v_add_u32_e32 v122, 0x410, v117
	ds_write2_b32 v122, v4, v5 offset1:1
	ds_write2_b32 v122, v6, v7 offset0:2 offset1:3
	s_waitcnt vmcnt(21)
	v_mul_f32_e32 v8, v66, v8
	v_mul_f32_e32 v9, v66, v9
	v_mul_f32_e32 v10, v66, v10
	v_mul_f32_e32 v11, v66, v11
	v_add_u32_e32 v122, 0x820, v117
	ds_write2_b32 v122, v8, v9 offset1:1
	ds_write2_b32 v122, v10, v11 offset0:2 offset1:3
	s_waitcnt vmcnt(20)
	v_mul_f32_e32 v12, v67, v12
	v_mul_f32_e32 v13, v67, v13
	v_mul_f32_e32 v14, v67, v14
	v_mul_f32_e32 v15, v67, v15
	v_add_u32_e32 v122, 0xc30, v117
	ds_write2_b32 v122, v12, v13 offset1:1
	ds_write2_b32 v122, v14, v15 offset0:2 offset1:3
	s_waitcnt vmcnt(19)
	v_mul_f32_e32 v16, v68, v16
	v_mul_f32_e32 v17, v68, v17
	v_mul_f32_e32 v18, v68, v18
	v_mul_f32_e32 v19, v68, v19
	v_add_u32_e32 v122, 0x1040, v117
	ds_write2_b32 v122, v16, v17 offset1:1
	ds_write2_b32 v122, v18, v19 offset0:2 offset1:3
	s_waitcnt vmcnt(18)
	v_mul_f32_e32 v20, v69, v20
	v_mul_f32_e32 v21, v69, v21
	v_mul_f32_e32 v22, v69, v22
	v_mul_f32_e32 v23, v69, v23
	v_add_u32_e32 v122, 0x1450, v117
	ds_write2_b32 v122, v20, v21 offset1:1
	ds_write2_b32 v122, v22, v23 offset0:2 offset1:3
	s_waitcnt vmcnt(17)
	v_mul_f32_e32 v24, v70, v24
	v_mul_f32_e32 v25, v70, v25
	v_mul_f32_e32 v26, v70, v26
	v_mul_f32_e32 v27, v70, v27
	v_add_u32_e32 v122, 0x1860, v117
	ds_write2_b32 v122, v24, v25 offset1:1
	ds_write2_b32 v122, v26, v27 offset0:2 offset1:3
	s_waitcnt vmcnt(16)
	v_mul_f32_e32 v28, v71, v28
	v_mul_f32_e32 v29, v71, v29
	v_mul_f32_e32 v30, v71, v30
	v_mul_f32_e32 v31, v71, v31
	v_add_u32_e32 v122, 0x1c70, v117
	ds_write2_b32 v122, v28, v29 offset1:1
	ds_write2_b32 v122, v30, v31 offset0:2 offset1:3
	s_waitcnt vmcnt(15)
	v_mul_f32_e32 v32, v72, v32
	v_mul_f32_e32 v33, v72, v33
	v_mul_f32_e32 v34, v72, v34
	v_mul_f32_e32 v35, v72, v35
	v_add_u32_e32 v122, 0x2080, v117
	ds_write2_b32 v122, v32, v33 offset1:1
	ds_write2_b32 v122, v34, v35 offset0:2 offset1:3
	s_waitcnt vmcnt(14)
	v_mul_f32_e32 v36, v73, v36
	v_mul_f32_e32 v37, v73, v37
	v_mul_f32_e32 v38, v73, v38
	v_mul_f32_e32 v39, v73, v39
	v_add_u32_e32 v122, 0x2490, v117
	ds_write2_b32 v122, v36, v37 offset1:1
	ds_write2_b32 v122, v38, v39 offset0:2 offset1:3
	s_waitcnt vmcnt(13)
	v_mul_f32_e32 v40, v74, v40
	v_mul_f32_e32 v41, v74, v41
	v_mul_f32_e32 v42, v74, v42
	v_mul_f32_e32 v43, v74, v43
	v_add_u32_e32 v122, 0x28a0, v117
	ds_write2_b32 v122, v40, v41 offset1:1
	ds_write2_b32 v122, v42, v43 offset0:2 offset1:3
	s_waitcnt vmcnt(12)
	v_mul_f32_e32 v44, v75, v44
	v_mul_f32_e32 v45, v75, v45
	v_mul_f32_e32 v46, v75, v46
	v_mul_f32_e32 v47, v75, v47
	v_add_u32_e32 v122, 0x2cb0, v117
	ds_write2_b32 v122, v44, v45 offset1:1
	ds_write2_b32 v122, v46, v47 offset0:2 offset1:3
	s_waitcnt vmcnt(11)
	v_mul_f32_e32 v48, v76, v48
	v_mul_f32_e32 v49, v76, v49
	v_mul_f32_e32 v50, v76, v50
	v_mul_f32_e32 v51, v76, v51
	v_add_u32_e32 v122, 0x30c0, v117
	ds_write2_b32 v122, v48, v49 offset1:1
	ds_write2_b32 v122, v50, v51 offset0:2 offset1:3
	s_waitcnt vmcnt(10)
	v_mul_f32_e32 v52, v77, v52
	v_mul_f32_e32 v53, v77, v53
	v_mul_f32_e32 v54, v77, v54
	v_mul_f32_e32 v55, v77, v55
	v_add_u32_e32 v122, 0x34d0, v117
	ds_write2_b32 v122, v52, v53 offset1:1
	ds_write2_b32 v122, v54, v55 offset0:2 offset1:3
	s_waitcnt vmcnt(9)
	v_mul_f32_e32 v56, v78, v56
	v_mul_f32_e32 v57, v78, v57
	v_mul_f32_e32 v58, v78, v58
	v_mul_f32_e32 v59, v78, v59
	v_add_u32_e32 v122, 0x38e0, v117
	ds_write2_b32 v122, v56, v57 offset1:1
	ds_write2_b32 v122, v58, v59 offset0:2 offset1:3
	s_waitcnt vmcnt(8)
	v_mul_f32_e32 v60, v79, v60
	v_mul_f32_e32 v61, v79, v61
	v_mul_f32_e32 v62, v79, v62
	v_mul_f32_e32 v63, v79, v63
	v_add_u32_e32 v122, 0x3cf0, v117
	ds_write2_b32 v122, v60, v61 offset1:1
	ds_write2_b32 v122, v62, v63 offset0:2 offset1:3
	s_branch .Lcva_wdone
.Lcva_wng:
	s_waitcnt vmcnt(23)
	ds_write2_b32 v117, v0, v1 offset1:1
	ds_write2_b32 v117, v2, v3 offset0:2 offset1:3
	s_waitcnt vmcnt(22)
	v_add_u32_e32 v122, 0x410, v117
	ds_write2_b32 v122, v4, v5 offset1:1
	ds_write2_b32 v122, v6, v7 offset0:2 offset1:3
	s_waitcnt vmcnt(21)
	v_add_u32_e32 v122, 0x820, v117
	ds_write2_b32 v122, v8, v9 offset1:1
	ds_write2_b32 v122, v10, v11 offset0:2 offset1:3
	s_waitcnt vmcnt(20)
	v_add_u32_e32 v122, 0xc30, v117
	ds_write2_b32 v122, v12, v13 offset1:1
	ds_write2_b32 v122, v14, v15 offset0:2 offset1:3
	s_waitcnt vmcnt(19)
	v_add_u32_e32 v122, 0x1040, v117
	ds_write2_b32 v122, v16, v17 offset1:1
	ds_write2_b32 v122, v18, v19 offset0:2 offset1:3
	s_waitcnt vmcnt(18)
	v_add_u32_e32 v122, 0x1450, v117
	ds_write2_b32 v122, v20, v21 offset1:1
	ds_write2_b32 v122, v22, v23 offset0:2 offset1:3
	s_waitcnt vmcnt(17)
	v_add_u32_e32 v122, 0x1860, v117
	ds_write2_b32 v122, v24, v25 offset1:1
	ds_write2_b32 v122, v26, v27 offset0:2 offset1:3
	s_waitcnt vmcnt(16)
	v_add_u32_e32 v122, 0x1c70, v117
	ds_write2_b32 v122, v28, v29 offset1:1
	ds_write2_b32 v122, v30, v31 offset0:2 offset1:3
	s_waitcnt vmcnt(15)
	v_add_u32_e32 v122, 0x2080, v117
	ds_write2_b32 v122, v32, v33 offset1:1
	ds_write2_b32 v122, v34, v35 offset0:2 offset1:3
	s_waitcnt vmcnt(14)
	v_add_u32_e32 v122, 0x2490, v117
	ds_write2_b32 v122, v36, v37 offset1:1
	ds_write2_b32 v122, v38, v39 offset0:2 offset1:3
	s_waitcnt vmcnt(13)
	v_add_u32_e32 v122, 0x28a0, v117
	ds_write2_b32 v122, v40, v41 offset1:1
	ds_write2_b32 v122, v42, v43 offset0:2 offset1:3
	s_waitcnt vmcnt(12)
	v_add_u32_e32 v122, 0x2cb0, v117
	ds_write2_b32 v122, v44, v45 offset1:1
	ds_write2_b32 v122, v46, v47 offset0:2 offset1:3
	s_waitcnt vmcnt(11)
	v_add_u32_e32 v122, 0x30c0, v117
	ds_write2_b32 v122, v48, v49 offset1:1
	ds_write2_b32 v122, v50, v51 offset0:2 offset1:3
	s_waitcnt vmcnt(10)
	v_add_u32_e32 v122, 0x34d0, v117
	ds_write2_b32 v122, v52, v53 offset1:1
	ds_write2_b32 v122, v54, v55 offset0:2 offset1:3
	s_waitcnt vmcnt(9)
	v_add_u32_e32 v122, 0x38e0, v117
	ds_write2_b32 v122, v56, v57 offset1:1
	ds_write2_b32 v122, v58, v59 offset0:2 offset1:3
	s_waitcnt vmcnt(8)
	v_add_u32_e32 v122, 0x3cf0, v117
	ds_write2_b32 v122, v60, v61 offset1:1
	ds_write2_b32 v122, v62, v63 offset0:2 offset1:3
.Lcva_wdone:
	s_waitcnt lgkmcnt(0)
	s_add_u32 s75, s60, s61
	s_mov_b32 s87, 0
	s_cmp_ge_u32 s75, s62
	s_cbranch_scc1 .Lcva_nonext
	s_mov_b32 s87, 1
	s_branch .Lcva_p1_m0

; #define LAS __attribute__((address_space(3)))
; __device__ __forceinline__ unsigned pk2(float lo, float hi) { return pg8::cvt_pk_bf16(lo, hi); }
; #define LDS_WAIT() asm volatile("s_waitcnt lgkmcnt(0)" ::: "memory")
; __device__ __forceinline__ void transpose_tile(const float* __restrict__ W, int K, int N, bf16* __restrict__ WT, const float* __restrict__ ga, const float* __restrict__ gb, int gsplit, LAS float* scr, int item, int lane) {
;     ...
;     const int kc = lane & 7;
; #pragma unroll
;     for (int j = 0; j < 8; ++j) { const int n = (lane >> 3) + 8 * j; const LAS float* sp = scr + (8 * kc) * 65 + n;
;         v4u o; o.x = pk2(sp[0 * 65], sp[1 * 65]); o.y = pk2(sp[2 * 65], sp[3 * 65]); o.z = pk2(sp[4 * 65], sp[5 * 65]); o.w = pk2(sp[6 * 65], sp[7 * 65]);
;         *(v4u*)(WT + (size_t)(n0 + n) * K + k0 + 8 * kc) = o; }
;     LDS_WAIT(); asm volatile("" ::: "memory");
; }
; __global__ void __launch_bounds__(NT, 2) fwd_mega(Args A) {
;     ...
;         for (int m = gw; m < T; m += NGW) {
;             const float* xrow = (m < 8192) ? A.xp + (size_t)m * D : A.xs + (size_t)(m - 8192) * D;
;             const f32x4* xr = (const f32x4*)xrow + lane; f32x4 v[8]; float s = 0.f;
; #pragma unroll
;             for (int j = 0; j < 8; ++j) { v[j] = __builtin_nontemporal_load(xr + 64 * j); s += (v[j][0] * v[j][0] + v[j][1] * v[j][1]) + (v[j][2] * v[j][2] + v[j][3] * v[j][3]); }
;             s = wave_sum(s);
.Lcva_p1_ng:
	global_load_dwordx4 v[0:3], v120, s[64:65] nt
	v_add_u32_e32 v120, s70, v120
	global_load_dwordx4 v[4:7], v120, s[64:65] nt
	v_add_u32_e32 v120, s70, v120
	global_load_dwordx4 v[8:11], v120, s[64:65] nt
	v_add_u32_e32 v120, s70, v120
	global_load_dwordx4 v[12:15], v120, s[64:65] nt
	v_add_u32_e32 v120, s70, v120
	global_load_dwordx4 v[16:19], v120, s[64:65] nt
	v_add_u32_e32 v120, s70, v120
	global_load_dwordx4 v[20:23], v120, s[64:65] nt
	v_add_u32_e32 v120, s70, v120
	global_load_dwordx4 v[24:27], v120, s[64:65] nt
	v_add_u32_e32 v120, s70, v120
	global_load_dwordx4 v[28:31], v120, s[64:65] nt
	v_add_u32_e32 v120, s70, v120
	global_load_dwordx4 v[32:35], v120, s[64:65] nt
	v_add_u32_e32 v120, s70, v120
	global_load_dwordx4 v[36:39], v120, s[64:65] nt
	v_add_u32_e32 v120, s70, v120
	global_load_dwordx4 v[40:43], v120, s[64:65] nt
	v_add_u32_e32 v120, s70, v120
	global_load_dwordx4 v[44:47], v120, s[64:65] nt
	v_add_u32_e32 v120, s70, v120
	global_load_dwordx4 v[48:51], v120, s[64:65] nt
	v_add_u32_e32 v120, s70, v120
	global_load_dwordx4 v[52:55], v120, s[64:65] nt
	v_add_u32_e32 v120, s70, v120
	global_load_dwordx4 v[56:59], v120, s[64:65] nt
	v_add_u32_e32 v120, s70, v120
	global_load_dwordx4 v[60:63], v120, s[64:65] nt
.Lcva_nonext:
	ds_read2_b32 v[80:81], v118 offset0:0 offset1:65
	ds_read2_b32 v[82:83], v118 offset0:130 offset1:195
	ds_read2_b32 v[84:85], v119 offset0:4 offset1:69
	ds_read2_b32 v[86:87], v119 offset0:134 offset1:199
	ds_read2_b32 v[88:89], v118 offset0:8 offset1:73
	ds_read2_b32 v[90:91], v118 offset0:138 offset1:203
	ds_read2_b32 v[92:93], v119 offset0:12 offset1:77
	ds_read2_b32 v[94:95], v119 offset0:142 offset1:207
	ds_read2_b32 v[96:97], v118 offset0:16 offset1:81
	ds_read2_b32 v[98:99], v118 offset0:146 offset1:211
	ds_read2_b32 v[100:101], v119 offset0:20 offset1:85
	ds_read2_b32 v[102:103], v119 offset0:150 offset1:215
	s_waitcnt lgkmcnt(8)
	v_cvt_pk_bf16_f32 v104, v80, v81
	v_cvt_pk_bf16_f32 v105, v82, v83
	v_cvt_pk_bf16_f32 v106, v84, v85
	v_cvt_pk_bf16_f32 v107, v86, v87
	global_store_dwordx4 v121, v[104:107], s[66:67]
	v_add_u32_e32 v121, s71, v121
	ds_read2_b32 v[80:81], v118 offset0:24 offset1:89
	ds_read2_b32 v[82:83], v118 offset0:154 offset1:219
	ds_read2_b32 v[84:85], v119 offset0:28 offset1:93
	ds_read2_b32 v[86:87], v119 offset0:158 offset1:223
	s_waitcnt lgkmcnt(8)
	v_cvt_pk_bf16_f32 v108, v88, v89
	v_cvt_pk_bf16_f32 v109, v90, v91
	v_cvt_pk_bf16_f32 v110, v92, v93
	v_cvt_pk_bf16_f32 v111, v94, v95
	global_store_dwordx4 v121, v[108:111], s[66:67]
	v_add_u32_e32 v121, s71, v121
	ds_read2_b32 v[88:89], v118 offset0:32 offset1:97
	ds_read2_b32 v[90:91], v118 offset0:162 offset1:227
	ds_read2_b32 v[92:93], v119 offset0:36 offset1:101
	ds_read2_b32 v[94:95], v119 offset0:166 offset1:231
	s_waitcnt lgkmcnt(8)
	v_cvt_pk_bf16_f32 v104, v96, v97
	v_cvt_pk_bf16_f32 v105, v98, v99
	v_cvt_pk_bf16_f32 v106, v100, v101
	v_cvt_pk_bf16_f32 v107, v102, v103
	global_store_dwordx4 v121, v[104:107], s[66:67]
	v_add_u32_e32 v121, s71, v121
	ds_read2_b32 v[96:97], v118 offset0:40 offset1:105
	ds_read2_b32 v[98:99], v118 offset0:170 offset1:235
	ds_read2_b32 v[100:101], v119 offset0:44 offset1:109
	ds_read2_b32 v[102:103], v119 offset0:174 offset1:239
	s_waitcnt lgkmcnt(8)
	v_cvt_pk_bf16_f32 v108, v80, v81
	v_cvt_pk_bf16_f32 v109, v82, v83
	v_cvt_pk_bf16_f32 v110, v84, v85
	v_cvt_pk_bf16_f32 v111, v86, v87
	global_store_dwordx4 v121, v[108:111], s[66:67]
	v_add_u32_e32 v121, s71, v121
	ds_read2_b32 v[80:81], v118 offset0:48 offset1:113
	ds_read2_b32 v[82:83], v118 offset0:178 offset1:243
	ds_read2_b32 v[84:85], v119 offset0:52 offset1:117
	ds_read2_b32 v[86:87], v119 offset0:182 offset1:247
	s_waitcnt lgkmcnt(8)
	v_cvt_pk_bf16_f32 v104, v88, v89
	v_cvt_pk_bf16_f32 v105, v90, v91
	v_cvt_pk_bf16_f32 v106, v92, v93
	v_cvt_pk_bf16_f32 v107, v94, v95
	global_store_dwordx4 v121, v[104:107], s[66:67]
	v_add_u32_e32 v121, s71, v121
	ds_read2_b32 v[88:89], v118 offset0:56 offset1:121
	ds_read2_b32 v[90:91], v118 offset0:186 offset1:251
	ds_read2_b32 v[92:93], v119 offset0:60 offset1:125
	ds_read2_b32 v[94:95], v119 offset0:190 offset1:255
	s_waitcnt lgkmcnt(8)
	v_cvt_pk_bf16_f32 v108, v96, v97
	v_cvt_pk_bf16_f32 v109, v98, v99
	v_cvt_pk_bf16_f32 v110, v100, v101
	v_cvt_pk_bf16_f32 v111, v102, v103
	global_store_dwordx4 v121, v[108:111], s[66:67]
	v_add_u32_e32 v121, s71, v121
	s_waitcnt lgkmcnt(4)
	v_cvt_pk_bf16_f32 v104, v80, v81
	v_cvt_pk_bf16_f32 v105, v82, v83
	v_cvt_pk_bf16_f32 v106, v84, v85
	v_cvt_pk_bf16_f32 v107, v86, v87
	global_store_dwordx4 v121, v[104:107], s[66:67]
	v_add_u32_e32 v121, s71, v121
	s_waitcnt lgkmcnt(0)
	v_cvt_pk_bf16_f32 v108, v88, v89
	v_cvt_pk_bf16_f32 v109, v90, v91
	v_cvt_pk_bf16_f32 v110, v92, v93
	v_cvt_pk_bf16_f32 v111, v94, v95
	global_store_dwordx4 v121, v[108:111], s[66:67]
	s_cmp_eq_u32 s87, 0
	s_cbranch_scc1 .Lcva_fin
	s_add_u32 s60, s60, s61
	s_branch .Lcva_tile
.Lcva_fin:
.Lcva_end:
.LBB0_59:
	s_cmpk_gt_i32 s58, 0x3fff
	v_mbcnt_lo_u32_b32 v161, -1, 0
	s_cbranch_scc1 .LBB0_64
	v_mbcnt_hi_u32_b32 v0, -1, v161
	v_and_b32_e32 v1, 64, v0
	v_add_u32_e32 v1, 64, v1
	v_xor_b32_e32 v2, 1, v0
	v_cmp_lt_i32_e32 vcc, v2, v1
	s_ashr_i32 s59, s58, 31
	s_lshl_b64 s[0:1], s[58:59], 12
	v_cndmask_b32_e32 v2, v0, v2, vcc
	v_lshlrev_b32_e32 v36, 2, v2
	v_xor_b32_e32 v2, 2, v0
	v_cmp_lt_i32_e32 vcc, v2, v1
	s_ashr_i32 s53, s52, 31
	v_lshl_or_b32 v34, v152, 3, s0
	v_cndmask_b32_e32 v2, v0, v2, vcc
	v_lshlrev_b32_e32 v37, 2, v2
	v_xor_b32_e32 v2, 4, v0
	v_cmp_lt_i32_e32 vcc, v2, v1
	v_mov_b32_e32 v35, s1
	s_lshl_b64 s[40:41], s[52:53], 12
	v_cndmask_b32_e32 v2, v0, v2, vcc
	v_lshlrev_b32_e32 v38, 2, v2
	v_xor_b32_e32 v2, 8, v0
	v_cmp_lt_i32_e32 vcc, v2, v1
	s_lshl_b64 s[0:1], s[58:59], 2
	s_add_u32 s0, s0, 0x30000
	v_cndmask_b32_e32 v2, v0, v2, vcc
	v_lshlrev_b32_e32 v39, 2, v2
	v_xor_b32_e32 v2, 16, v0
	v_cmp_lt_i32_e32 vcc, v2, v1
	v_mov_b32_e32 v33, 0
	v_cmp_eq_u32_e64 s[4:5], 0, v152
	v_cndmask_b32_e32 v2, v0, v2, vcc
	v_lshlrev_b32_e32 v40, 2, v2
	v_xor_b32_e32 v2, 32, v0
	v_cmp_lt_i32_e32 vcc, v2, v1
	s_addc_u32 s1, s1, 0
	s_lshl_b64 s[42:43], s[52:53], 2
	v_cndmask_b32_e32 v0, v0, v2, vcc
	v_lshlrev_b32_e32 v41, 2, v0
	v_lshlrev_b32_e32 v32, 4, v152
	s_movk_i32 s62, 0x1000
	v_mov_b32_e32 v42, 0x358637bd
	s_mov_b32 s63, 0xf800000
	v_mov_b32_e32 v43, 0x260
	s_branch .LBB0_62

; #define LAS __attribute__((address_space(3)))
; __device__ __forceinline__ void transpose_tile(const float* __restrict__ W, int K, int N, bf16* __restrict__ WT, const float* __restrict__ ga, const float* __restrict__ gb, int gsplit, LAS float* scr, int item, int lane) {
;     const int nkb = K / 64, nb = item / nkb, kb = item % nkb, k0 = 64 * kb, n0 = 64 * nb;
;     const int c = lane & 15, kq = lane >> 4;
;     f32x4 v[16];
; #pragma unroll
;     for (int i = 0; i < 16; ++i) v[i] = __builtin_nontemporal_load((const f32x4*)(W + (size_t)(k0 + 4 * i + kq) * N + n0 + 4 * c));
; #pragma unroll
;     for (int i = 0; i < 16; ++i) {
;         const int k = k0 + 4 * i + kq; float g = 1.0f; if (ga) g = (k < gsplit) ? ga[k] : gb[k - gsplit];
;         LAS float* p = scr + (4 * i + kq) * 65 + 4 * c; p[0] = v[i][0] * g; p[1] = v[i][1] * g; p[2] = v[i][2] * g; p[3] = v[i][3] * g;
; __global__ void __launch_bounds__(NT, 2) fwd_mega(Args A) {
;     ...
;             constexpr int I_UP = (D / 64) * (FF / 64);
;             LAS float* scr = (LAS float*)(lds + wave * 16640);
;             for (int it = hi * NW + wave; it < I_UP; it += NH * NW) transpose_tile(A.w_up, D, FF, WupT, A.g_ffn, A.g_ffn, D, scr, it, lane);
.LBB0_464:
	s_add_u32 s8, s28, 0x1900000
	s_addc_u32 s9, s29, 0
	s_abs_i32 s0, s30
	v_cvt_f32_u32_e32 v0, s0
	s_sub_i32 s1, 0, s0
	v_rcp_iflag_f32_e32 v0, v0
	s_nop 0
	v_mul_f32_e32 v0, 0x4f7ffffe, v0
	v_cvt_u32_f32_e32 v0, v0
	s_nop 0
	v_readfirstlane_b32 s2, v0
	s_mul_i32 s1, s1, s2
	s_mul_hi_u32 s1, s2, s1
	s_add_i32 s2, s2, s1
	s_mul_hi_u32 s1, s2, 0x380
	s_mul_i32 s1, s1, s0
	s_sub_i32 s1, 0x380, s1
	s_sub_i32 s2, s1, s0
	s_cmp_ge_u32 s1, s0
	s_cselect_b32 s1, s2, s1
	s_sub_i32 s2, s1, s0
	s_cmp_ge_u32 s1, s0
	s_cselect_b32 s1, s2, s1
	s_sub_i32 s0, s12, s1
	s_cmp_lt_i32 s0, 0
	s_cbranch_scc1 .LBB0_501
	s_lshl_b32 s0, s0, 3
	v_readlane_b32 s2, v255, 3
	s_sub_i32 s4, s30, s1
	s_nop 1
	s_add_i32 s60, s0, s2
	s_lshl_b32 s61, s4, 3
	s_movk_i32 s62, 0x1c00
	s_cmp_ge_u32 s60, s62
	s_cbranch_scc1 .Lcvb_end
	v_readlane_b32 s63, v255, 3
	v_and_b32_e32 v122, 63, v160
	v_and_b32_e32 v112, 15, v122
	v_lshlrev_b32_e32 v112, 4, v112
	v_lshrrev_b32_e32 v113, 4, v122
	v_lshlrev_b32_e32 v114, 2, v113
	v_and_b32_e32 v115, 7, v122
	v_lshrrev_b32_e32 v116, 3, v122
	s_mulk_i32 s63, 0x4100
	s_movk_i32 s80, 0x104
	v_mad_u32_u24 v117, v113, s80, v112
	v_add_u32_e32 v117, s63, v117
	s_movk_i32 s80, 0x820
	v_lshlrev_b32_e32 v119, 2, v116
	v_mad_u32_u24 v118, v115, s80, v119
	v_add_u32_e32 v118, s63, v118
	v_add_u32_e32 v119, 0x400, v118
	v_lshlrev_b32_e32 v115, 4, v115
	s_mov_b32 s75, s60
	s_cmp_lt_u32 s75, 0x1000
	s_cbranch_scc1 .Lcvb_p0_m0
	s_cmp_lt_u32 s75, 0x1400
	s_cbranch_scc1 .Lcvb_p0_m1
	s_branch .Lcvb_p0_m2
.Lcvb_p0_m0:
	s_mov_b32 s80, s75
	s_lshr_b32 s81, s80, 5
	s_and_b32 s82, s80, 0x1f
	s_lshl_b32 s81, s81, 6
	s_lshl_b32 s82, s82, 6
	s_mul_i32 s83, s82, 0x2000
	s_add_u32 s83, s83, s81
	s_lshl_b32 s83, s83, 2
	s_add_u32 s64, s22, s83
	s_addc_u32 s65, s23, 0
	s_lshl_b32 s84, s81, 11
	s_add_u32 s84, s84, s82
	s_lshl_b32 s84, s84, 1
	s_add_u32 s84, s84, 0x1900000
	s_add_u32 s76, s28, s84
	s_addc_u32 s77, s29, 0
	s_mov_b32 s70, 0x20000
	s_mov_b32 s78, 0x8000
	s_mov_b32 s72, 0x8000
	s_mov_b32 s85, 0x1000
	s_mov_b32 s79, 1
	s_lshl_b32 s86, s82, 2
	s_add_u32 s68, s20, s86
	s_addc_u32 s69, s21, 0
	v_mad_u32_u24 v120, v113, s72, v112
	v_mad_u32_u24 v124, v116, s85, v115
	s_branch .Lcvb_p0_pd
.Lcvb_p0_m1:
	s_sub_u32 s80, s75, 0x1000
	s_lshr_b32 s81, s80, 5
	s_and_b32 s82, s80, 0x1f
	s_lshl_b32 s81, s81, 6
	s_lshl_b32 s82, s82, 6
	s_mul_i32 s83, s82, 0x800
	s_add_u32 s83, s83, s81
	s_lshl_b32 s83, s83, 2
	s_add_u32 s64, s18, s83
	s_addc_u32 s65, s19, 0
	s_lshl_b32 s84, s81, 11
	s_add_u32 s84, s84, s82
	s_lshl_b32 s84, s84, 1
	s_add_u32 s84, s84, 0x1100000
	s_add_u32 s76, s28, s84
	s_addc_u32 s77, s29, 0
	s_mov_b32 s70, 0x8000
	s_mov_b32 s78, 0x8000
	s_mov_b32 s72, 0x2000
	s_mov_b32 s85, 0x1000
	s_mov_b32 s79, 1
	s_lshl_b32 s86, s82, 2
	s_cmp_lt_u32 s82, 0x400
	s_cbranch_scc1 .Lcvb_p0_m1_ga
	s_sub_u32 s86, s86, 0x1000
	s_add_u32 s68, s16, s86
	s_addc_u32 s69, s17, 0
	s_branch .Lcvb_p0_m1_gd
.Lcvb_p0_m1_ga:
	s_add_u32 s68, s14, s86
	s_addc_u32 s69, s15, 0
.Lcvb_p0_m1_gd:
	v_mad_u32_u24 v120, v113, s72, v112
	v_mad_u32_u24 v124, v116, s85, v115
	s_branch .Lcvb_p0_pd
.Lcvb_p0_m2:
	s_sub_u32 s80, s75, 0x1400
	s_lshr_b32 s81, s80, 7
	s_and_b32 s82, s80, 0x7f
	s_lshl_b32 s81, s81, 6
	s_lshl_b32 s82, s82, 6
	s_mul_i32 s83, s82, 0x800
	s_add_u32 s83, s83, s81
	s_lshl_b32 s83, s83, 2
	s_add_u32 s64, s24, s83
	s_addc_u32 s65, s25, 0
	s_lshl_b32 s84, s81, 13
	s_add_u32 s84, s84, s82
	s_lshl_b32 s84, s84, 1
	s_add_u32 s84, s84, 0x3900000
	s_add_u32 s76, s28, s84
	s_addc_u32 s77, s29, 0
	s_mov_b32 s70, 0x8000
	s_mov_b32 s78, 0x20000
	s_mov_b32 s72, 0x2000
	s_mov_b32 s85, 0x4000
	s_mov_b32 s79, 0
	v_mad_u32_u24 v120, v113, s72, v112
	v_mad_u32_u24 v124, v116, s85, v115

; #define LAS __attribute__((address_space(3)))
; __device__ __forceinline__ void transpose_tile(const float* __restrict__ W, int K, int N, bf16* __restrict__ WT, const float* __restrict__ ga, const float* __restrict__ gb, int gsplit, LAS float* scr, int item, int lane) {
;     const int nkb = K / 64, nb = item / nkb, kb = item % nkb, k0 = 64 * kb, n0 = 64 * nb;
; __global__ void __launch_bounds__(NT, 2) fwd_mega(Args A) {
;     ...
;             for (int it = hi * NW + wave; it < I_UP; it += NH * NW) transpose_tile(A.w_up, D, FF, WupT, A.g_ffn, A.g_ffn, D, scr, it, lane);
.Lcvb_wdone:
	s_waitcnt lgkmcnt(0)
	s_add_u32 s75, s60, s61
	s_mov_b32 s87, 0
	s_cmp_ge_u32 s75, s62
	s_cbranch_scc1 .Lcvb_nonext
	s_mov_b32 s87, 1
	s_cmp_lt_u32 s75, 0x1000
	s_cbranch_scc1 .Lcvb_p1_m0
	s_cmp_lt_u32 s75, 0x1400
	s_cbranch_scc1 .Lcvb_p1_m1
	s_branch .Lcvb_p1_m2

; __global__ void __launch_bounds__(NT, 2) fwd_mega(Args A) {
;     ...
;             for (int it = hi * NW + wave; it < I_UP; it += NH * NW) transpose_tile(A.w_up, D, FF, WupT, A.g_ffn, A.g_ffn, D, scr, it, lane);
;         }
;     }
;     xcd_barrier(xbar);
.Lcvb_fin:
.Lcvb_end:
.LBB0_500:
	v_readlane_b32 s88, v255, 1
	v_readlane_b32 s89, v255, 2

; #define LAS __attribute__((address_space(3)))
; __device__ __forceinline__ void convert_out_down(const Args& A, LAS unsigned char* lds, int vcu, int G) {
;     int tid = threadIdx.x; asm volatile("" : "+v"(tid)); const int lane = tid & 63, wave = __builtin_amdgcn_readfirstlane(tid >> 6);
;     unsigned char* ws = A.ws;
;     __syncthreads();
;     LAS float* scr = (LAS float*)(lds + wave * 16640);
;     constexpr int I_OUT0 = (D / 64) * (D / 64), I_DN0 = (FF / 64) * (D / 64);
;     for (int it = vcu * NW + wave; it < I_OUT0 + I_DN0; it += G * NW) {
;         if (it < I_OUT0) transpose_tile(A.w_out, D, D, (bf16*)(ws + WS_WOUT), A.g_ao, A.g_go, 1024, scr, it, lane);
;         else transpose_tile(A.w_down, FF, D, (bf16*)(ws + WS_WDOWN), nullptr, nullptr, 0, scr, it - I_OUT0, lane);
;     }
;     __syncthreads();
; __global__ void __launch_bounds__(NT, 2) fwd_mega(Args A) {
;     ...
;     if (!(vcu2 & 1)) convert_out_down(A, lds, vcu2, G);
.LBB0_553:
	s_or_b64 exec, exec, s[2:3]
	s_add_u32 s6, s28, 0x1100000
	s_addc_u32 s7, s29, 0
	s_bitcmp1_b32 s96, 0
	s_cselect_b64 s[22:23], -1, 0
	s_and_b64 vcc, exec, s[22:23]
	s_waitcnt lgkmcnt(0)
	s_barrier
	s_cbranch_vccnz .LBB0_594
	s_lshl_b32 s0, s96, 3
	v_readlane_b32 s2, v255, 3
	s_nop 3
	s_add_i32 s60, s0, s2
	s_mov_b32 s61, s52
	s_movk_i32 s62, 0x800
	s_cmp_ge_u32 s60, s62
	s_cbranch_scc1 .Lcvc_end
	v_readlane_b32 s63, v255, 3
	v_and_b32_e32 v122, 63, v160
	v_and_b32_e32 v112, 15, v122
	v_lshlrev_b32_e32 v112, 4, v112
	v_lshrrev_b32_e32 v113, 4, v122
	v_lshlrev_b32_e32 v114, 2, v113
	v_and_b32_e32 v115, 7, v122
	v_lshrrev_b32_e32 v116, 3, v122
	s_mulk_i32 s63, 0x4100
	s_movk_i32 s80, 0x104
	v_mad_u32_u24 v117, v113, s80, v112
	v_add_u32_e32 v117, s63, v117
	s_movk_i32 s80, 0x820
	v_lshlrev_b32_e32 v119, 2, v116
	v_mad_u32_u24 v118, v115, s80, v119
	v_add_u32_e32 v118, s63, v118
	v_add_u32_e32 v119, 0x400, v118
	v_lshlrev_b32_e32 v115, 4, v115
	s_mov_b32 s75, s60
	s_branch .Lcvc_p0_m0
.Lcvc_p0_m0:
	s_mov_b32 s80, s75
	s_add_u32 s80, s80, 0x800
	s_lshr_b32 s81, s80, 7
	s_and_b32 s82, s80, 0x7f
	s_lshl_b32 s81, s81, 6
	s_lshl_b32 s82, s82, 6
	s_mul_i32 s83, s82, 0x800
	s_add_u32 s83, s83, s81
	s_lshl_b32 s83, s83, 2
	s_add_u32 s64, s24, s83
	s_addc_u32 s65, s25, 0
	s_lshl_b32 s84, s81, 13
	s_add_u32 s84, s84, s82
	s_lshl_b32 s84, s84, 1
	s_add_u32 s84, s84, 0x3900000
	s_add_u32 s76, s28, s84
	s_addc_u32 s77, s29, 0
	s_mov_b32 s70, 0x8000
	s_mov_b32 s78, 0x20000
	s_mov_b32 s72, 0x2000
	s_mov_b32 s85, 0x4000
	s_mov_b32 s79, 0
	v_mad_u32_u24 v120, v113, s72, v112
	v_mad_u32_u24 v124, v116, s85, v115

; #define LAS __attribute__((address_space(3)))
; __device__ __forceinline__ void attn_unit(const bf16* proj, unsigned char* ws, LAS unsigned char* lds, int a) {
;     int tid = threadIdx.x; asm volatile("" : "+v"(tid)); const int lane = tid & 63, wave = __builtin_amdgcn_readfirstlane(tid >> 6);
;     const float* par = (const float*)(ws + WS_PAR);
;     bf16* mix = (bf16*)(ws + WS_MIX); float* ssmix = (float*)(ws + WS_SSMIX);
;     const int gb = a >> 2, kvh = (a >> 1) & 1, hp = a & 1;
;     int n, nb; if (gb < 64) { nb = 32; n = gb & 31; } else { nb = 16; n = (gb - 64) & 15; }
;     const int tok0 = gb * 128, hw = wave >> 2, rq = wave & 3, fr = lane & 15, fq = lane >> 4;
;     const int h0 = kvh * 4 + hp * 2, h = h0 + hw;
;     LAS unsigned char* QS = lds + LQ; LAS unsigned char* KS = lds + LK; LAS unsigned char* VS = lds + LV;
; __global__ void __launch_bounds__(NT, 2) fwd_mega(Args A) {
;     ...
; #pragma unroll 1
;     for (int u = vcu2; u < 1536; u += G) {
;         if (u < 512) attn_unit(PROJ, ws, lds, u);
;         else gmlp_unit(PROJ, ws, lds, u - 512);
;     }
.Lcvc_fin:
.Lcvc_end:
.LBB0_594:
	s_add_u32 s10, s28, 0x9900000
	s_addc_u32 s11, s29, 0
	s_add_u32 s20, s28, 0x40000
	s_addc_u32 s21, s29, 0
	s_cmpk_gt_i32 s96, 0x5ff
	s_cbranch_scc1 .LBB0_621
	s_add_u32 s42, s28, 0x1c0000
	s_addc_u32 s43, s29, 0
	s_add_u32 s47, s28, 0x200800
	s_addc_u32 s53, s29, 0
	v_mbcnt_hi_u32_b32 v167, -1, v161
	s_add_u32 s58, s28, 0x201800
	v_and_b32_e32 v0, 64, v167
	s_addc_u32 s59, s29, 0
	s_mov_b32 s45, 0
	v_mov_b32_e32 v163, 0
	s_movk_i32 s60, 0x1c00
	s_mov_b32 s46, 0x3a800000
	s_mov_b32 s61, 0xf800000
	v_mov_b32_e32 v166, 0x260
	s_movk_i32 s62, 0x120
	s_mov_b64 s[48:49], 0x9900800
	s_mov_b32 s63, 0x9900000
	s_movk_i32 s64, 0x110
	s_add_i32 s65, 0, 0x11000
	s_add_i32 s66, 0, 0x19800
	s_mov_b32 s67, 0xf149f2ca
	v_xor_b32_e32 v168, 16, v167
	v_add_u32_e32 v169, 64, v0
	v_xor_b32_e32 v170, 32, v167
	v_mov_b32_e32 v171, 0xf149f2ca
	s_mov_b32 s68, s96
	s_branch .LBB0_598

; #define LAS __attribute__((address_space(3)))
; __device__ __forceinline__ void convert_out_down(const Args& A, LAS unsigned char* lds, int vcu, int G) {
;     int tid = threadIdx.x; asm volatile("" : "+v"(tid)); const int lane = tid & 63, wave = __builtin_amdgcn_readfirstlane(tid >> 6);
;     unsigned char* ws = A.ws;
;     __syncthreads();
;     LAS float* scr = (LAS float*)(lds + wave * 16640);
;     constexpr int I_OUT0 = (D / 64) * (D / 64), I_DN0 = (FF / 64) * (D / 64);
;     for (int it = vcu * NW + wave; it < I_OUT0 + I_DN0; it += G * NW) {
;         if (it < I_OUT0) transpose_tile(A.w_out, D, D, (bf16*)(ws + WS_WOUT), A.g_ao, A.g_go, 1024, scr, it, lane);
;         else transpose_tile(A.w_down, FF, D, (bf16*)(ws + WS_WDOWN), nullptr, nullptr, 0, scr, it - I_OUT0, lane);
;     }
;     __syncthreads();
; __global__ void __launch_bounds__(NT, 2) fwd_mega(Args A) {
;     ...
;     if (vcu2 & 1) convert_out_down(A, lds, vcu2, G);
.LBB0_621:
	s_and_b64 vcc, exec, s[22:23]
	s_cbranch_vccz .LBB0_662
	s_waitcnt lgkmcnt(0)
	s_barrier
	s_lshl_b32 s0, s96, 3
	v_readlane_b32 s2, v255, 3
	s_nop 3
	s_add_i32 s60, s0, s2
	s_mov_b32 s61, s52
	s_movk_i32 s62, 0x800
	s_cmp_ge_u32 s60, s62
	s_cbranch_scc1 .Lcvd_end
	v_readlane_b32 s63, v255, 3
	v_and_b32_e32 v122, 63, v160
	v_and_b32_e32 v112, 15, v122
	v_lshlrev_b32_e32 v112, 4, v112
	v_lshrrev_b32_e32 v113, 4, v122
	v_lshlrev_b32_e32 v114, 2, v113
	v_and_b32_e32 v115, 7, v122
	v_lshrrev_b32_e32 v116, 3, v122
	s_mulk_i32 s63, 0x4100
	s_movk_i32 s80, 0x104
	v_mad_u32_u24 v117, v113, s80, v112
	v_add_u32_e32 v117, s63, v117
	s_movk_i32 s80, 0x820
	v_lshlrev_b32_e32 v119, 2, v116
	v_mad_u32_u24 v118, v115, s80, v119
	v_add_u32_e32 v118, s63, v118
	v_add_u32_e32 v119, 0x400, v118
	v_lshlrev_b32_e32 v115, 4, v115
	s_mov_b32 s75, s60
	s_branch .Lcvd_p0_m0

; __device__ __forceinline__ unsigned xb_add(unsigned* p, unsigned v) { return __hip_atomic_fetch_add(p, v, __ATOMIC_RELAXED, __HIP_MEMORY_SCOPE_AGENT); }
; __device__ __forceinline__ void xcd_barrier(const XcdBarrier& b) {
;     asm volatile("s_waitcnt vmcnt(0)" ::: "memory");
;     __syncthreads();
;     if (threadIdx.x == 0) {
;         unsigned* bar = b.bar;
;         __builtin_amdgcn_s_waitcnt(0);
;         unsigned nloc = b.st[0], nx = b.st[1];
;         if (nloc == 0u) { xcd_barrier_complete(bar, b.x, nloc, nx); b.st[0] = nloc; b.st[1] = nx; }
;         const unsigned old = xb_add(&bar[XB_XSUB(b.x)], 1u);
; __global__ void __launch_bounds__(NT, 2) fwd_mega(Args A) {
;     ...
;     xcd_barrier(xbar);
.Lcvd_fin:
.Lcvd_end:
.LBB0_662:
	s_waitcnt vmcnt(0)
	s_waitcnt lgkmcnt(0)
	s_barrier
	s_and_saveexec_b64 s[2:3], s[88:89]
	s_cbranch_execz .LBB0_714
	s_add_i32 s0, 0, 0x23fc0
	v_mov_b32_e32 v0, s0
	s_waitcnt vmcnt(0) expcnt(0) lgkmcnt(0)
	ds_read_b32 v2, v0
	s_add_i32 s0, 0, 0x23fc4
	v_mov_b32_e32 v0, s0
	ds_read_b32 v0, v0
	s_waitcnt lgkmcnt(1)
	v_cmp_ne_u32_e32 vcc, 0, v2
	s_cbranch_vccnz .LBB0_678
	s_add_u32 s4, s28, 0x210200
	s_addc_u32 s5, s29, 0
	s_add_u32 s14, s28, 0x210400
	s_addc_u32 s15, s29, 0
	s_add_u32 s16, s28, 0x210500
	s_addc_u32 s17, s29, 0
	s_add_u32 s18, s28, 0x210600
	s_addc_u32 s19, s29, 0
	s_add_u32 s22, s28, 0x210700
	s_addc_u32 s23, s29, 0
	s_add_u32 s24, s28, 0x210800
	s_addc_u32 s25, s29, 0
	s_add_u32 s40, s28, 0x210900
	s_addc_u32 s41, s29, 0
	s_add_u32 s42, s28, 0x210a00
	s_addc_u32 s43, s29, 0
	s_add_u32 s44, s28, 0x210b00
	s_addc_u32 s45, s29, 0
	s_add_u32 s46, s28, 0x210c00
	s_addc_u32 s47, s29, 0
	s_add_u32 s48, s28, 0x210d00
	s_addc_u32 s49, s29, 0
	s_add_u32 s50, s28, 0x210e00
	s_addc_u32 s51, s29, 0
	s_add_u32 s52, s28, 0x210f00
	s_addc_u32 s53, s29, 0
	s_add_u32 s54, s28, 0x211000
	s_addc_u32 s55, s29, 0
	s_add_u32 s56, s28, 0x211100
	s_addc_u32 s57, s29, 0
	s_add_u32 s58, s28, 0x211200
	v_readlane_b32 s0, v255, 0
	s_addc_u32 s59, s29, 0
	s_mul_i32 s0, s31, s0
	s_add_u32 s60, s28, 0x211300
	s_mul_i32 s0, s0, s30
	s_addc_u32 s61, s29, 0
	s_mov_b32 s1, 1
	v_mov_b32_e32 v16, 0
	s_branch .LBB0_666
